# SwiGLU epilogue: the four full-rate f32 ops per output as packed v_pk_mul_f32/v_pk_add_f32 on register pairs (exp2/rcp unchanged, same op order, f32)
# speedup vs baseline: 1.0058x; 1.0058x over previous
.LBB0_357:
	s_mov_b32 s100, 0xbfb8aa3b
	v_pk_mul_f32 v[166:167], v[126:127], s[100:101] op_sel_hi:[1,0]
	v_pk_mul_f32 v[168:169], v[128:129], s[100:101] op_sel_hi:[1,0]
	v_pk_mul_f32 v[170:171], v[122:123], s[100:101] op_sel_hi:[1,0]
	v_pk_mul_f32 v[172:173], v[124:125], s[100:101] op_sel_hi:[1,0]
	v_exp_f32_e32 v166, v166
	v_exp_f32_e32 v167, v167
	v_exp_f32_e32 v168, v168
	v_exp_f32_e32 v169, v169
	v_exp_f32_e32 v170, v170
	v_exp_f32_e32 v171, v171
	v_exp_f32_e32 v172, v172
	v_exp_f32_e32 v173, v173
	v_pk_add_f32 v[166:167], v[166:167], 1.0 op_sel_hi:[1,0]
	v_pk_add_f32 v[168:169], v[168:169], 1.0 op_sel_hi:[1,0]
	v_pk_add_f32 v[170:171], v[170:171], 1.0 op_sel_hi:[1,0]
	v_pk_add_f32 v[172:173], v[172:173], 1.0 op_sel_hi:[1,0]
	v_rcp_f32_e32 v166, v166
	v_rcp_f32_e32 v167, v167
	v_rcp_f32_e32 v168, v168
	v_rcp_f32_e32 v169, v169
	v_rcp_f32_e32 v170, v170
	v_rcp_f32_e32 v171, v171
	v_rcp_f32_e32 v172, v172
	v_rcp_f32_e32 v173, v173
	v_pk_mul_f32 v[166:167], v[126:127], v[166:167]
	v_pk_mul_f32 v[168:169], v[128:129], v[168:169]
	v_pk_mul_f32 v[170:171], v[122:123], v[170:171]
	v_pk_mul_f32 v[172:173], v[124:125], v[172:173]
	v_pk_mul_f32 v[166:167], v[166:167], v[118:119]
	v_pk_mul_f32 v[168:169], v[168:169], v[120:121]
	v_pk_mul_f32 v[170:171], v[170:171], v[114:115]
	v_pk_mul_f32 v[172:173], v[172:173], v[116:117]
	s_lshl_b32 s3, s43, 1
	s_mul_i32 s2, s24, 44
	s_or_b32 s3, s3, s40
	s_add_i32 s2, s3, s2
	s_ashr_i32 s3, s2, 31
	s_lshl_b64 s[2:3], s[2:3], 15
	v_lshl_add_u64 v[148:149], v[140:141], 0, s[2:3]
	v_cvt_pk_bf16_f32 v114, v166, v167
	v_cvt_pk_bf16_f32 v115, v168, v169
	v_cvt_pk_bf16_f32 v116, v170, v171
	v_cvt_pk_bf16_f32 v117, v172, v173
	global_store_dwordx4 v[148:149], v[114:117], off
	v_pk_mul_f32 v[166:167], v[110:111], s[100:101] op_sel_hi:[1,0]
	v_pk_mul_f32 v[168:169], v[112:113], s[100:101] op_sel_hi:[1,0]
	v_pk_mul_f32 v[170:171], v[106:107], s[100:101] op_sel_hi:[1,0]
	v_pk_mul_f32 v[172:173], v[108:109], s[100:101] op_sel_hi:[1,0]
	v_exp_f32_e32 v166, v166
	v_exp_f32_e32 v167, v167
	v_exp_f32_e32 v168, v168
	v_exp_f32_e32 v169, v169
	v_exp_f32_e32 v170, v170
	v_exp_f32_e32 v171, v171
	v_exp_f32_e32 v172, v172
	v_exp_f32_e32 v173, v173
	v_pk_add_f32 v[166:167], v[166:167], 1.0 op_sel_hi:[1,0]
	v_pk_add_f32 v[168:169], v[168:169], 1.0 op_sel_hi:[1,0]
	v_pk_add_f32 v[170:171], v[170:171], 1.0 op_sel_hi:[1,0]
	v_pk_add_f32 v[172:173], v[172:173], 1.0 op_sel_hi:[1,0]
	v_rcp_f32_e32 v166, v166
	v_rcp_f32_e32 v167, v167
	v_rcp_f32_e32 v168, v168
	v_rcp_f32_e32 v169, v169
	v_rcp_f32_e32 v170, v170
	v_rcp_f32_e32 v171, v171
	v_rcp_f32_e32 v172, v172
	v_rcp_f32_e32 v173, v173
	v_pk_mul_f32 v[166:167], v[110:111], v[166:167]
	v_pk_mul_f32 v[168:169], v[112:113], v[168:169]
	v_pk_mul_f32 v[170:171], v[106:107], v[170:171]
	v_pk_mul_f32 v[172:173], v[108:109], v[172:173]
	v_pk_mul_f32 v[166:167], v[166:167], v[102:103]
	v_pk_mul_f32 v[168:169], v[168:169], v[104:105]
	v_pk_mul_f32 v[170:171], v[170:171], v[98:99]
	v_pk_mul_f32 v[172:173], v[172:173], v[100:101]
	s_movk_i32 s2, 0x1000
	v_cvt_pk_bf16_f32 v98, v166, v167
	v_cvt_pk_bf16_f32 v99, v168, v169
	v_cvt_pk_bf16_f32 v100, v170, v171
	v_cvt_pk_bf16_f32 v101, v172, v173
	global_store_dwordx4 v[148:149], v[98:101], off offset:2048
	v_pk_mul_f32 v[166:167], v[94:95], s[100:101] op_sel_hi:[1,0]
	v_pk_mul_f32 v[168:169], v[96:97], s[100:101] op_sel_hi:[1,0]
	v_pk_mul_f32 v[170:171], v[90:91], s[100:101] op_sel_hi:[1,0]
	v_pk_mul_f32 v[172:173], v[92:93], s[100:101] op_sel_hi:[1,0]
	v_exp_f32_e32 v166, v166
	v_exp_f32_e32 v167, v167
	v_exp_f32_e32 v168, v168
	v_exp_f32_e32 v169, v169
	v_exp_f32_e32 v170, v170
	v_exp_f32_e32 v171, v171
	v_exp_f32_e32 v172, v172
	v_exp_f32_e32 v173, v173
	v_pk_add_f32 v[166:167], v[166:167], 1.0 op_sel_hi:[1,0]
	v_pk_add_f32 v[168:169], v[168:169], 1.0 op_sel_hi:[1,0]
	v_pk_add_f32 v[170:171], v[170:171], 1.0 op_sel_hi:[1,0]
	v_pk_add_f32 v[172:173], v[172:173], 1.0 op_sel_hi:[1,0]
	v_rcp_f32_e32 v166, v166
	v_rcp_f32_e32 v167, v167
	v_rcp_f32_e32 v168, v168
	v_rcp_f32_e32 v169, v169
	v_rcp_f32_e32 v170, v170
	v_rcp_f32_e32 v171, v171
	v_rcp_f32_e32 v172, v172
	v_rcp_f32_e32 v173, v173
	v_pk_mul_f32 v[166:167], v[94:95], v[166:167]
	v_pk_mul_f32 v[168:169], v[96:97], v[168:169]
	v_pk_mul_f32 v[170:171], v[90:91], v[170:171]
	v_pk_mul_f32 v[172:173], v[92:93], v[172:173]
	v_pk_mul_f32 v[166:167], v[166:167], v[86:87]
	v_pk_mul_f32 v[168:169], v[168:169], v[88:89]
	v_pk_mul_f32 v[170:171], v[170:171], v[82:83]
	v_pk_mul_f32 v[172:173], v[172:173], v[84:85]
	v_add_co_u32_e32 v86, vcc, s2, v148
	s_nop 1
	v_addc_co_u32_e32 v87, vcc, 0, v149, vcc
	v_cvt_pk_bf16_f32 v82, v166, v167
	v_cvt_pk_bf16_f32 v83, v168, v169
	v_cvt_pk_bf16_f32 v84, v170, v171
	v_cvt_pk_bf16_f32 v85, v172, v173
	global_store_dwordx4 v[86:87], v[82:85], off
	v_pk_mul_f32 v[166:167], v[78:79], s[100:101] op_sel_hi:[1,0]
	v_pk_mul_f32 v[168:169], v[80:81], s[100:101] op_sel_hi:[1,0]
	v_pk_mul_f32 v[170:171], v[74:75], s[100:101] op_sel_hi:[1,0]
	v_pk_mul_f32 v[172:173], v[76:77], s[100:101] op_sel_hi:[1,0]
	v_exp_f32_e32 v166, v166
	v_exp_f32_e32 v167, v167
	v_exp_f32_e32 v168, v168
	v_exp_f32_e32 v169, v169
	v_exp_f32_e32 v170, v170
	v_exp_f32_e32 v171, v171
	v_exp_f32_e32 v172, v172
	v_exp_f32_e32 v173, v173
	v_pk_add_f32 v[166:167], v[166:167], 1.0 op_sel_hi:[1,0]
	v_pk_add_f32 v[168:169], v[168:169], 1.0 op_sel_hi:[1,0]
	v_pk_add_f32 v[170:171], v[170:171], 1.0 op_sel_hi:[1,0]
	v_pk_add_f32 v[172:173], v[172:173], 1.0 op_sel_hi:[1,0]
	v_rcp_f32_e32 v166, v166
	v_rcp_f32_e32 v167, v167
	v_rcp_f32_e32 v168, v168
	v_rcp_f32_e32 v169, v169
	v_rcp_f32_e32 v170, v170
	v_rcp_f32_e32 v171, v171
	v_rcp_f32_e32 v172, v172
	v_rcp_f32_e32 v173, v173
	v_pk_mul_f32 v[166:167], v[78:79], v[166:167]
	v_pk_mul_f32 v[168:169], v[80:81], v[168:169]
	v_pk_mul_f32 v[170:171], v[74:75], v[170:171]
	v_pk_mul_f32 v[172:173], v[76:77], v[172:173]
	v_pk_mul_f32 v[166:167], v[166:167], v[70:71]
	v_pk_mul_f32 v[168:169], v[168:169], v[72:73]
	v_pk_mul_f32 v[170:171], v[170:171], v[66:67]
	v_pk_mul_f32 v[172:173], v[172:173], v[68:69]
	s_movk_i32 s2, 0x4000
	v_cvt_pk_bf16_f32 v66, v166, v167
	v_cvt_pk_bf16_f32 v67, v168, v169
	v_cvt_pk_bf16_f32 v68, v170, v171
	v_cvt_pk_bf16_f32 v69, v172, v173
	global_store_dwordx4 v[86:87], v[66:69], off offset:2048
	v_pk_mul_f32 v[166:167], v[62:63], s[100:101] op_sel_hi:[1,0]
	v_pk_mul_f32 v[168:169], v[64:65], s[100:101] op_sel_hi:[1,0]
	v_pk_mul_f32 v[170:171], v[58:59], s[100:101] op_sel_hi:[1,0]
	v_pk_mul_f32 v[172:173], v[60:61], s[100:101] op_sel_hi:[1,0]
	v_exp_f32_e32 v166, v166
	v_exp_f32_e32 v167, v167
	v_exp_f32_e32 v168, v168
	v_exp_f32_e32 v169, v169
	v_exp_f32_e32 v170, v170
	v_exp_f32_e32 v171, v171
	v_exp_f32_e32 v172, v172
	v_exp_f32_e32 v173, v173
	v_pk_add_f32 v[166:167], v[166:167], 1.0 op_sel_hi:[1,0]
	v_pk_add_f32 v[168:169], v[168:169], 1.0 op_sel_hi:[1,0]
	v_pk_add_f32 v[170:171], v[170:171], 1.0 op_sel_hi:[1,0]
	v_pk_add_f32 v[172:173], v[172:173], 1.0 op_sel_hi:[1,0]
	v_rcp_f32_e32 v166, v166
	v_rcp_f32_e32 v167, v167
	v_rcp_f32_e32 v168, v168
	v_rcp_f32_e32 v169, v169
	v_rcp_f32_e32 v170, v170
	v_rcp_f32_e32 v171, v171
	v_rcp_f32_e32 v172, v172
	v_rcp_f32_e32 v173, v173
	v_pk_mul_f32 v[166:167], v[62:63], v[166:167]
	v_pk_mul_f32 v[168:169], v[64:65], v[168:169]
	v_pk_mul_f32 v[170:171], v[58:59], v[170:171]
	v_pk_mul_f32 v[172:173], v[60:61], v[172:173]
	v_pk_mul_f32 v[166:167], v[166:167], v[54:55]
	v_pk_mul_f32 v[168:169], v[168:169], v[56:57]
	v_pk_mul_f32 v[170:171], v[170:171], v[50:51]
	v_pk_mul_f32 v[172:173], v[172:173], v[52:53]
	v_add_co_u32_e32 v54, vcc, s2, v148
	s_nop 1
	v_addc_co_u32_e32 v55, vcc, 0, v149, vcc
	s_movk_i32 s2, 0x5000
	v_add_co_u32_e32 v56, vcc, s2, v148
	s_nop 0
	s_nop 1
	v_addc_co_u32_e32 v57, vcc, 0, v149, vcc
	v_cvt_pk_bf16_f32 v50, v166, v167
	v_cvt_pk_bf16_f32 v51, v168, v169
	v_cvt_pk_bf16_f32 v52, v170, v171
	v_cvt_pk_bf16_f32 v53, v172, v173
	global_store_dwordx4 v[56:57], v[50:53], off offset:-4096
	v_pk_mul_f32 v[166:167], v[46:47], s[100:101] op_sel_hi:[1,0]
	v_pk_mul_f32 v[168:169], v[48:49], s[100:101] op_sel_hi:[1,0]
	v_pk_mul_f32 v[170:171], v[42:43], s[100:101] op_sel_hi:[1,0]
	v_pk_mul_f32 v[172:173], v[44:45], s[100:101] op_sel_hi:[1,0]
	v_exp_f32_e32 v166, v166
	v_exp_f32_e32 v167, v167
	v_exp_f32_e32 v168, v168
	v_exp_f32_e32 v169, v169
	v_exp_f32_e32 v170, v170
	v_exp_f32_e32 v171, v171
	v_exp_f32_e32 v172, v172
	v_exp_f32_e32 v173, v173
	v_pk_add_f32 v[166:167], v[166:167], 1.0 op_sel_hi:[1,0]
	v_pk_add_f32 v[168:169], v[168:169], 1.0 op_sel_hi:[1,0]
	v_pk_add_f32 v[170:171], v[170:171], 1.0 op_sel_hi:[1,0]
	v_pk_add_f32 v[172:173], v[172:173], 1.0 op_sel_hi:[1,0]
	v_rcp_f32_e32 v166, v166
	v_rcp_f32_e32 v167, v167
	v_rcp_f32_e32 v168, v168
	v_rcp_f32_e32 v169, v169
	v_rcp_f32_e32 v170, v170
	v_rcp_f32_e32 v171, v171
	v_rcp_f32_e32 v172, v172
	v_rcp_f32_e32 v173, v173
	v_pk_mul_f32 v[166:167], v[46:47], v[166:167]
	v_pk_mul_f32 v[168:169], v[48:49], v[168:169]
	v_pk_mul_f32 v[170:171], v[42:43], v[170:171]
	v_pk_mul_f32 v[172:173], v[44:45], v[172:173]
	v_pk_mul_f32 v[166:167], v[166:167], v[38:39]
	v_pk_mul_f32 v[168:169], v[168:169], v[40:41]
	v_pk_mul_f32 v[170:171], v[170:171], v[34:35]
	v_pk_mul_f32 v[172:173], v[172:173], v[36:37]
	s_andn2_b64 vcc, exec, s[18:19]
	v_cvt_pk_bf16_f32 v34, v166, v167
	v_cvt_pk_bf16_f32 v35, v168, v169
	v_cvt_pk_bf16_f32 v36, v170, v171
	v_cvt_pk_bf16_f32 v37, v172, v173
	global_store_dwordx4 v[54:55], v[34:37], off offset:2048
	v_pk_mul_f32 v[166:167], v[30:31], s[100:101] op_sel_hi:[1,0]
	v_pk_mul_f32 v[168:169], v[32:33], s[100:101] op_sel_hi:[1,0]
	v_pk_mul_f32 v[170:171], v[26:27], s[100:101] op_sel_hi:[1,0]
	v_pk_mul_f32 v[172:173], v[28:29], s[100:101] op_sel_hi:[1,0]
	v_exp_f32_e32 v166, v166
	v_exp_f32_e32 v167, v167
	v_exp_f32_e32 v168, v168
	v_exp_f32_e32 v169, v169
	v_exp_f32_e32 v170, v170
	v_exp_f32_e32 v171, v171
	v_exp_f32_e32 v172, v172
	v_exp_f32_e32 v173, v173
	v_pk_add_f32 v[166:167], v[166:167], 1.0 op_sel_hi:[1,0]
	v_pk_add_f32 v[168:169], v[168:169], 1.0 op_sel_hi:[1,0]
	v_pk_add_f32 v[170:171], v[170:171], 1.0 op_sel_hi:[1,0]
	v_pk_add_f32 v[172:173], v[172:173], 1.0 op_sel_hi:[1,0]
	v_rcp_f32_e32 v166, v166
	v_rcp_f32_e32 v167, v167
	v_rcp_f32_e32 v168, v168
	v_rcp_f32_e32 v169, v169
	v_rcp_f32_e32 v170, v170
	v_rcp_f32_e32 v171, v171
	v_rcp_f32_e32 v172, v172
	v_rcp_f32_e32 v173, v173
	v_pk_mul_f32 v[166:167], v[30:31], v[166:167]
	v_pk_mul_f32 v[168:169], v[32:33], v[168:169]
	v_pk_mul_f32 v[170:171], v[26:27], v[170:171]
	v_pk_mul_f32 v[172:173], v[28:29], v[172:173]
	v_pk_mul_f32 v[166:167], v[166:167], v[22:23]
	v_pk_mul_f32 v[168:169], v[168:169], v[24:25]
	v_pk_mul_f32 v[170:171], v[170:171], v[18:19]
	v_pk_mul_f32 v[172:173], v[172:173], v[20:21]
	s_mov_b64 s[2:3], -1
	v_cvt_pk_bf16_f32 v18, v166, v167
	v_cvt_pk_bf16_f32 v19, v168, v169
	v_cvt_pk_bf16_f32 v20, v170, v171
	v_cvt_pk_bf16_f32 v21, v172, v173
	global_store_dwordx4 v[56:57], v[18:21], off
	v_pk_mul_f32 v[166:167], v[14:15], s[100:101] op_sel_hi:[1,0]
	v_pk_mul_f32 v[168:169], v[16:17], s[100:101] op_sel_hi:[1,0]
	v_pk_mul_f32 v[170:171], v[10:11], s[100:101] op_sel_hi:[1,0]
	v_pk_mul_f32 v[172:173], v[12:13], s[100:101] op_sel_hi:[1,0]
	v_exp_f32_e32 v166, v166
	v_exp_f32_e32 v167, v167
	v_exp_f32_e32 v168, v168
	v_exp_f32_e32 v169, v169
	v_exp_f32_e32 v170, v170
	v_exp_f32_e32 v171, v171
	v_exp_f32_e32 v172, v172
	v_exp_f32_e32 v173, v173
	v_pk_add_f32 v[166:167], v[166:167], 1.0 op_sel_hi:[1,0]
	v_pk_add_f32 v[168:169], v[168:169], 1.0 op_sel_hi:[1,0]
	v_pk_add_f32 v[170:171], v[170:171], 1.0 op_sel_hi:[1,0]
	v_pk_add_f32 v[172:173], v[172:173], 1.0 op_sel_hi:[1,0]
	v_rcp_f32_e32 v166, v166
	v_rcp_f32_e32 v167, v167
	v_rcp_f32_e32 v168, v168
	v_rcp_f32_e32 v169, v169
	v_rcp_f32_e32 v170, v170
	v_rcp_f32_e32 v171, v171
	v_rcp_f32_e32 v172, v172
	v_rcp_f32_e32 v173, v173
	v_pk_mul_f32 v[166:167], v[14:15], v[166:167]
	v_pk_mul_f32 v[168:169], v[16:17], v[168:169]
	v_pk_mul_f32 v[170:171], v[10:11], v[170:171]
	v_pk_mul_f32 v[172:173], v[12:13], v[172:173]
	v_pk_mul_f32 v[166:167], v[166:167], v[6:7]
	v_pk_mul_f32 v[168:169], v[168:169], v[8:9]
	v_pk_mul_f32 v[170:171], v[170:171], v[2:3]
	v_pk_mul_f32 v[172:173], v[172:173], v[4:5]
	v_cvt_pk_bf16_f32 v2, v166, v167
	v_cvt_pk_bf16_f32 v3, v168, v169
	v_cvt_pk_bf16_f32 v4, v170, v171
	v_cvt_pk_bf16_f32 v5, v172, v173
	global_store_dwordx4 v[56:57], v[2:5], off offset:2048
	s_cbranch_vccnz .LBB0_349
	s_andn2_b64 vcc, exec, s[0:1]
	s_cbranch_vccnz .LBB0_348
	s_barrier
	s_branch .LBB0_348

.LBB0_454:
	s_mov_b32 s100, 0xbfb8aa3b
	v_pk_mul_f32 v[152:153], v[126:127], s[100:101] op_sel_hi:[1,0]
	v_pk_mul_f32 v[154:155], v[128:129], s[100:101] op_sel_hi:[1,0]
	v_pk_mul_f32 v[156:157], v[122:123], s[100:101] op_sel_hi:[1,0]
	v_pk_mul_f32 v[158:159], v[124:125], s[100:101] op_sel_hi:[1,0]
	v_exp_f32_e32 v152, v152
	v_exp_f32_e32 v153, v153
	v_exp_f32_e32 v154, v154
	v_exp_f32_e32 v155, v155
	v_exp_f32_e32 v156, v156
	v_exp_f32_e32 v157, v157
	v_exp_f32_e32 v158, v158
	v_exp_f32_e32 v159, v159
	v_pk_add_f32 v[152:153], v[152:153], 1.0 op_sel_hi:[1,0]
	v_pk_add_f32 v[154:155], v[154:155], 1.0 op_sel_hi:[1,0]
	v_pk_add_f32 v[156:157], v[156:157], 1.0 op_sel_hi:[1,0]
	v_pk_add_f32 v[158:159], v[158:159], 1.0 op_sel_hi:[1,0]
	v_rcp_f32_e32 v152, v152
	v_rcp_f32_e32 v153, v153
	v_rcp_f32_e32 v154, v154
	v_rcp_f32_e32 v155, v155
	v_rcp_f32_e32 v156, v156
	v_rcp_f32_e32 v157, v157
	v_rcp_f32_e32 v158, v158
	v_rcp_f32_e32 v159, v159
	v_pk_mul_f32 v[152:153], v[126:127], v[152:153]
	v_pk_mul_f32 v[154:155], v[128:129], v[154:155]
	v_pk_mul_f32 v[156:157], v[122:123], v[156:157]
	v_pk_mul_f32 v[158:159], v[124:125], v[158:159]
	v_pk_mul_f32 v[152:153], v[152:153], v[118:119]
	v_pk_mul_f32 v[154:155], v[154:155], v[120:121]
	v_pk_mul_f32 v[156:157], v[156:157], v[114:115]
	v_pk_mul_f32 v[158:159], v[158:159], v[116:117]
	s_lshl_b32 s3, s24, 1
	s_mul_i32 s2, s26, 44
	s_or_b32 s3, s3, s41
	s_add_i32 s2, s3, s2
	s_ashr_i32 s3, s2, 31
	s_lshl_b64 s[2:3], s[2:3], 15
	v_lshl_add_u64 v[146:147], v[138:139], 0, s[2:3]
	v_cvt_pk_bf16_f32 v114, v152, v153
	v_cvt_pk_bf16_f32 v115, v154, v155
	v_cvt_pk_bf16_f32 v116, v156, v157
	v_cvt_pk_bf16_f32 v117, v158, v159
	global_store_dwordx4 v[146:147], v[114:117], off
	v_pk_mul_f32 v[152:153], v[110:111], s[100:101] op_sel_hi:[1,0]
	v_pk_mul_f32 v[154:155], v[112:113], s[100:101] op_sel_hi:[1,0]
	v_pk_mul_f32 v[156:157], v[106:107], s[100:101] op_sel_hi:[1,0]
	v_pk_mul_f32 v[158:159], v[108:109], s[100:101] op_sel_hi:[1,0]
	v_exp_f32_e32 v152, v152
	v_exp_f32_e32 v153, v153
	v_exp_f32_e32 v154, v154
	v_exp_f32_e32 v155, v155
	v_exp_f32_e32 v156, v156
	v_exp_f32_e32 v157, v157
	v_exp_f32_e32 v158, v158
	v_exp_f32_e32 v159, v159
	v_pk_add_f32 v[152:153], v[152:153], 1.0 op_sel_hi:[1,0]
	v_pk_add_f32 v[154:155], v[154:155], 1.0 op_sel_hi:[1,0]
	v_pk_add_f32 v[156:157], v[156:157], 1.0 op_sel_hi:[1,0]
	v_pk_add_f32 v[158:159], v[158:159], 1.0 op_sel_hi:[1,0]
	v_rcp_f32_e32 v152, v152
	v_rcp_f32_e32 v153, v153
	v_rcp_f32_e32 v154, v154
	v_rcp_f32_e32 v155, v155
	v_rcp_f32_e32 v156, v156
	v_rcp_f32_e32 v157, v157
	v_rcp_f32_e32 v158, v158
	v_rcp_f32_e32 v159, v159
	v_pk_mul_f32 v[152:153], v[110:111], v[152:153]
	v_pk_mul_f32 v[154:155], v[112:113], v[154:155]
	v_pk_mul_f32 v[156:157], v[106:107], v[156:157]
	v_pk_mul_f32 v[158:159], v[108:109], v[158:159]
	v_pk_mul_f32 v[152:153], v[152:153], v[102:103]
	v_pk_mul_f32 v[154:155], v[154:155], v[104:105]
	v_pk_mul_f32 v[156:157], v[156:157], v[98:99]
	v_pk_mul_f32 v[158:159], v[158:159], v[100:101]
	s_movk_i32 s2, 0x1000
	v_cvt_pk_bf16_f32 v98, v152, v153
	v_cvt_pk_bf16_f32 v99, v154, v155
	v_cvt_pk_bf16_f32 v100, v156, v157
	v_cvt_pk_bf16_f32 v101, v158, v159
	global_store_dwordx4 v[146:147], v[98:101], off offset:2048
	v_pk_mul_f32 v[152:153], v[94:95], s[100:101] op_sel_hi:[1,0]
	v_pk_mul_f32 v[154:155], v[96:97], s[100:101] op_sel_hi:[1,0]
	v_pk_mul_f32 v[156:157], v[90:91], s[100:101] op_sel_hi:[1,0]
	v_pk_mul_f32 v[158:159], v[92:93], s[100:101] op_sel_hi:[1,0]
	v_exp_f32_e32 v152, v152
	v_exp_f32_e32 v153, v153
	v_exp_f32_e32 v154, v154
	v_exp_f32_e32 v155, v155
	v_exp_f32_e32 v156, v156
	v_exp_f32_e32 v157, v157
	v_exp_f32_e32 v158, v158
	v_exp_f32_e32 v159, v159
	v_pk_add_f32 v[152:153], v[152:153], 1.0 op_sel_hi:[1,0]
	v_pk_add_f32 v[154:155], v[154:155], 1.0 op_sel_hi:[1,0]
	v_pk_add_f32 v[156:157], v[156:157], 1.0 op_sel_hi:[1,0]
	v_pk_add_f32 v[158:159], v[158:159], 1.0 op_sel_hi:[1,0]
	v_rcp_f32_e32 v152, v152
	v_rcp_f32_e32 v153, v153
	v_rcp_f32_e32 v154, v154
	v_rcp_f32_e32 v155, v155
	v_rcp_f32_e32 v156, v156
	v_rcp_f32_e32 v157, v157
	v_rcp_f32_e32 v158, v158
	v_rcp_f32_e32 v159, v159
	v_pk_mul_f32 v[152:153], v[94:95], v[152:153]
	v_pk_mul_f32 v[154:155], v[96:97], v[154:155]
	v_pk_mul_f32 v[156:157], v[90:91], v[156:157]
	v_pk_mul_f32 v[158:159], v[92:93], v[158:159]
	v_pk_mul_f32 v[152:153], v[152:153], v[86:87]
	v_pk_mul_f32 v[154:155], v[154:155], v[88:89]
	v_pk_mul_f32 v[156:157], v[156:157], v[82:83]
	v_pk_mul_f32 v[158:159], v[158:159], v[84:85]
	v_add_co_u32_e32 v86, vcc, s2, v146
	s_nop 1
	v_addc_co_u32_e32 v87, vcc, 0, v147, vcc
	v_cvt_pk_bf16_f32 v82, v152, v153
	v_cvt_pk_bf16_f32 v83, v154, v155
	v_cvt_pk_bf16_f32 v84, v156, v157
	v_cvt_pk_bf16_f32 v85, v158, v159
	global_store_dwordx4 v[86:87], v[82:85], off
	v_pk_mul_f32 v[152:153], v[78:79], s[100:101] op_sel_hi:[1,0]
	v_pk_mul_f32 v[154:155], v[80:81], s[100:101] op_sel_hi:[1,0]
	v_pk_mul_f32 v[156:157], v[74:75], s[100:101] op_sel_hi:[1,0]
	v_pk_mul_f32 v[158:159], v[76:77], s[100:101] op_sel_hi:[1,0]
	v_exp_f32_e32 v152, v152
	v_exp_f32_e32 v153, v153
	v_exp_f32_e32 v154, v154
	v_exp_f32_e32 v155, v155
	v_exp_f32_e32 v156, v156
	v_exp_f32_e32 v157, v157
	v_exp_f32_e32 v158, v158
	v_exp_f32_e32 v159, v159
	v_pk_add_f32 v[152:153], v[152:153], 1.0 op_sel_hi:[1,0]
	v_pk_add_f32 v[154:155], v[154:155], 1.0 op_sel_hi:[1,0]
	v_pk_add_f32 v[156:157], v[156:157], 1.0 op_sel_hi:[1,0]
	v_pk_add_f32 v[158:159], v[158:159], 1.0 op_sel_hi:[1,0]
	v_rcp_f32_e32 v152, v152
	v_rcp_f32_e32 v153, v153
	v_rcp_f32_e32 v154, v154
	v_rcp_f32_e32 v155, v155
	v_rcp_f32_e32 v156, v156
	v_rcp_f32_e32 v157, v157
	v_rcp_f32_e32 v158, v158
	v_rcp_f32_e32 v159, v159
	v_pk_mul_f32 v[152:153], v[78:79], v[152:153]
	v_pk_mul_f32 v[154:155], v[80:81], v[154:155]
	v_pk_mul_f32 v[156:157], v[74:75], v[156:157]
	v_pk_mul_f32 v[158:159], v[76:77], v[158:159]
	v_pk_mul_f32 v[152:153], v[152:153], v[70:71]
	v_pk_mul_f32 v[154:155], v[154:155], v[72:73]
	v_pk_mul_f32 v[156:157], v[156:157], v[66:67]
	v_pk_mul_f32 v[158:159], v[158:159], v[68:69]
	s_movk_i32 s2, 0x4000
	v_cvt_pk_bf16_f32 v66, v152, v153
	v_cvt_pk_bf16_f32 v67, v154, v155
	v_cvt_pk_bf16_f32 v68, v156, v157
	v_cvt_pk_bf16_f32 v69, v158, v159
	global_store_dwordx4 v[86:87], v[66:69], off offset:2048
	v_pk_mul_f32 v[152:153], v[62:63], s[100:101] op_sel_hi:[1,0]
	v_pk_mul_f32 v[154:155], v[64:65], s[100:101] op_sel_hi:[1,0]
	v_pk_mul_f32 v[156:157], v[58:59], s[100:101] op_sel_hi:[1,0]
	v_pk_mul_f32 v[158:159], v[60:61], s[100:101] op_sel_hi:[1,0]
	v_exp_f32_e32 v152, v152
	v_exp_f32_e32 v153, v153
	v_exp_f32_e32 v154, v154
	v_exp_f32_e32 v155, v155
	v_exp_f32_e32 v156, v156
	v_exp_f32_e32 v157, v157
	v_exp_f32_e32 v158, v158
	v_exp_f32_e32 v159, v159
	v_pk_add_f32 v[152:153], v[152:153], 1.0 op_sel_hi:[1,0]
	v_pk_add_f32 v[154:155], v[154:155], 1.0 op_sel_hi:[1,0]
	v_pk_add_f32 v[156:157], v[156:157], 1.0 op_sel_hi:[1,0]
	v_pk_add_f32 v[158:159], v[158:159], 1.0 op_sel_hi:[1,0]
	v_rcp_f32_e32 v152, v152
	v_rcp_f32_e32 v153, v153
	v_rcp_f32_e32 v154, v154
	v_rcp_f32_e32 v155, v155
	v_rcp_f32_e32 v156, v156
	v_rcp_f32_e32 v157, v157
	v_rcp_f32_e32 v158, v158
	v_rcp_f32_e32 v159, v159
	v_pk_mul_f32 v[152:153], v[62:63], v[152:153]
	v_pk_mul_f32 v[154:155], v[64:65], v[154:155]
	v_pk_mul_f32 v[156:157], v[58:59], v[156:157]
	v_pk_mul_f32 v[158:159], v[60:61], v[158:159]
	v_pk_mul_f32 v[152:153], v[152:153], v[54:55]
	v_pk_mul_f32 v[154:155], v[154:155], v[56:57]
	v_pk_mul_f32 v[156:157], v[156:157], v[50:51]
	v_pk_mul_f32 v[158:159], v[158:159], v[52:53]
	v_add_co_u32_e32 v54, vcc, s2, v146
	s_nop 1
	v_addc_co_u32_e32 v55, vcc, 0, v147, vcc
	s_movk_i32 s2, 0x5000
	v_add_co_u32_e32 v56, vcc, s2, v146
	s_nop 0
	s_nop 1
	v_addc_co_u32_e32 v57, vcc, 0, v147, vcc
	v_cvt_pk_bf16_f32 v50, v152, v153
	v_cvt_pk_bf16_f32 v51, v154, v155
	v_cvt_pk_bf16_f32 v52, v156, v157
	v_cvt_pk_bf16_f32 v53, v158, v159
	global_store_dwordx4 v[56:57], v[50:53], off offset:-4096
	v_pk_mul_f32 v[152:153], v[46:47], s[100:101] op_sel_hi:[1,0]
	v_pk_mul_f32 v[154:155], v[48:49], s[100:101] op_sel_hi:[1,0]
	v_pk_mul_f32 v[156:157], v[42:43], s[100:101] op_sel_hi:[1,0]
	v_pk_mul_f32 v[158:159], v[44:45], s[100:101] op_sel_hi:[1,0]
	v_exp_f32_e32 v152, v152
	v_exp_f32_e32 v153, v153
	v_exp_f32_e32 v154, v154
	v_exp_f32_e32 v155, v155
	v_exp_f32_e32 v156, v156
	v_exp_f32_e32 v157, v157
	v_exp_f32_e32 v158, v158
	v_exp_f32_e32 v159, v159
	v_pk_add_f32 v[152:153], v[152:153], 1.0 op_sel_hi:[1,0]
	v_pk_add_f32 v[154:155], v[154:155], 1.0 op_sel_hi:[1,0]
	v_pk_add_f32 v[156:157], v[156:157], 1.0 op_sel_hi:[1,0]
	v_pk_add_f32 v[158:159], v[158:159], 1.0 op_sel_hi:[1,0]
	v_rcp_f32_e32 v152, v152
	v_rcp_f32_e32 v153, v153
	v_rcp_f32_e32 v154, v154
	v_rcp_f32_e32 v155, v155
	v_rcp_f32_e32 v156, v156
	v_rcp_f32_e32 v157, v157
	v_rcp_f32_e32 v158, v158
	v_rcp_f32_e32 v159, v159
	v_pk_mul_f32 v[152:153], v[46:47], v[152:153]
	v_pk_mul_f32 v[154:155], v[48:49], v[154:155]
	v_pk_mul_f32 v[156:157], v[42:43], v[156:157]
	v_pk_mul_f32 v[158:159], v[44:45], v[158:159]
	v_pk_mul_f32 v[152:153], v[152:153], v[38:39]
	v_pk_mul_f32 v[154:155], v[154:155], v[40:41]
	v_pk_mul_f32 v[156:157], v[156:157], v[34:35]
	v_pk_mul_f32 v[158:159], v[158:159], v[36:37]
	s_andn2_b64 vcc, exec, s[18:19]
	v_cvt_pk_bf16_f32 v34, v152, v153
	v_cvt_pk_bf16_f32 v35, v154, v155
	v_cvt_pk_bf16_f32 v36, v156, v157
	v_cvt_pk_bf16_f32 v37, v158, v159
	global_store_dwordx4 v[54:55], v[34:37], off offset:2048
	v_pk_mul_f32 v[152:153], v[30:31], s[100:101] op_sel_hi:[1,0]
	v_pk_mul_f32 v[154:155], v[32:33], s[100:101] op_sel_hi:[1,0]
	v_pk_mul_f32 v[156:157], v[26:27], s[100:101] op_sel_hi:[1,0]
	v_pk_mul_f32 v[158:159], v[28:29], s[100:101] op_sel_hi:[1,0]
	v_exp_f32_e32 v152, v152
	v_exp_f32_e32 v153, v153
	v_exp_f32_e32 v154, v154
	v_exp_f32_e32 v155, v155
	v_exp_f32_e32 v156, v156
	v_exp_f32_e32 v157, v157
	v_exp_f32_e32 v158, v158
	v_exp_f32_e32 v159, v159
	v_pk_add_f32 v[152:153], v[152:153], 1.0 op_sel_hi:[1,0]
	v_pk_add_f32 v[154:155], v[154:155], 1.0 op_sel_hi:[1,0]
	v_pk_add_f32 v[156:157], v[156:157], 1.0 op_sel_hi:[1,0]
	v_pk_add_f32 v[158:159], v[158:159], 1.0 op_sel_hi:[1,0]
	v_rcp_f32_e32 v152, v152
	v_rcp_f32_e32 v153, v153
	v_rcp_f32_e32 v154, v154
	v_rcp_f32_e32 v155, v155
	v_rcp_f32_e32 v156, v156
	v_rcp_f32_e32 v157, v157
	v_rcp_f32_e32 v158, v158
	v_rcp_f32_e32 v159, v159
	v_pk_mul_f32 v[152:153], v[30:31], v[152:153]
	v_pk_mul_f32 v[154:155], v[32:33], v[154:155]
	v_pk_mul_f32 v[156:157], v[26:27], v[156:157]
	v_pk_mul_f32 v[158:159], v[28:29], v[158:159]
	v_pk_mul_f32 v[152:153], v[152:153], v[22:23]
	v_pk_mul_f32 v[154:155], v[154:155], v[24:25]
	v_pk_mul_f32 v[156:157], v[156:157], v[18:19]
	v_pk_mul_f32 v[158:159], v[158:159], v[20:21]
	s_mov_b64 s[2:3], -1
	v_cvt_pk_bf16_f32 v18, v152, v153
	v_cvt_pk_bf16_f32 v19, v154, v155
	v_cvt_pk_bf16_f32 v20, v156, v157
	v_cvt_pk_bf16_f32 v21, v158, v159
	global_store_dwordx4 v[56:57], v[18:21], off
	v_pk_mul_f32 v[152:153], v[14:15], s[100:101] op_sel_hi:[1,0]
	v_pk_mul_f32 v[154:155], v[16:17], s[100:101] op_sel_hi:[1,0]
	v_pk_mul_f32 v[156:157], v[10:11], s[100:101] op_sel_hi:[1,0]
	v_pk_mul_f32 v[158:159], v[12:13], s[100:101] op_sel_hi:[1,0]
	v_exp_f32_e32 v152, v152
	v_exp_f32_e32 v153, v153
	v_exp_f32_e32 v154, v154
	v_exp_f32_e32 v155, v155
	v_exp_f32_e32 v156, v156
	v_exp_f32_e32 v157, v157
	v_exp_f32_e32 v158, v158
	v_exp_f32_e32 v159, v159
	v_pk_add_f32 v[152:153], v[152:153], 1.0 op_sel_hi:[1,0]
	v_pk_add_f32 v[154:155], v[154:155], 1.0 op_sel_hi:[1,0]
	v_pk_add_f32 v[156:157], v[156:157], 1.0 op_sel_hi:[1,0]
	v_pk_add_f32 v[158:159], v[158:159], 1.0 op_sel_hi:[1,0]
	v_rcp_f32_e32 v152, v152
	v_rcp_f32_e32 v153, v153
	v_rcp_f32_e32 v154, v154
	v_rcp_f32_e32 v155, v155
	v_rcp_f32_e32 v156, v156
	v_rcp_f32_e32 v157, v157
	v_rcp_f32_e32 v158, v158
	v_rcp_f32_e32 v159, v159
	v_pk_mul_f32 v[152:153], v[14:15], v[152:153]
	v_pk_mul_f32 v[154:155], v[16:17], v[154:155]
	v_pk_mul_f32 v[156:157], v[10:11], v[156:157]
	v_pk_mul_f32 v[158:159], v[12:13], v[158:159]
	v_pk_mul_f32 v[152:153], v[152:153], v[6:7]
	v_pk_mul_f32 v[154:155], v[154:155], v[8:9]
	v_pk_mul_f32 v[156:157], v[156:157], v[2:3]
	v_pk_mul_f32 v[158:159], v[158:159], v[4:5]
	v_cvt_pk_bf16_f32 v2, v152, v153
	v_cvt_pk_bf16_f32 v3, v154, v155
	v_cvt_pk_bf16_f32 v4, v156, v157
	v_cvt_pk_bf16_f32 v5, v158, v159
	global_store_dwordx4 v[56:57], v[2:5], off offset:2048
	s_cbranch_vccnz .LBB0_446
	s_andn2_b64 vcc, exec, s[0:1]
	s_cbranch_vccnz .LBB0_445
	s_barrier
	s_branch .LBB0_445

.LBB0_1306:
	s_mov_b32 s100, 0xbfb8aa3b
	v_pk_mul_f32 v[166:167], v[126:127], s[100:101] op_sel_hi:[1,0]
	v_pk_mul_f32 v[168:169], v[128:129], s[100:101] op_sel_hi:[1,0]
	v_pk_mul_f32 v[170:171], v[122:123], s[100:101] op_sel_hi:[1,0]
	v_pk_mul_f32 v[172:173], v[124:125], s[100:101] op_sel_hi:[1,0]
	v_exp_f32_e32 v166, v166
	v_exp_f32_e32 v167, v167
	v_exp_f32_e32 v168, v168
	v_exp_f32_e32 v169, v169
	v_exp_f32_e32 v170, v170
	v_exp_f32_e32 v171, v171
	v_exp_f32_e32 v172, v172
	v_exp_f32_e32 v173, v173
	v_pk_add_f32 v[166:167], v[166:167], 1.0 op_sel_hi:[1,0]
	v_pk_add_f32 v[168:169], v[168:169], 1.0 op_sel_hi:[1,0]
	v_pk_add_f32 v[170:171], v[170:171], 1.0 op_sel_hi:[1,0]
	v_pk_add_f32 v[172:173], v[172:173], 1.0 op_sel_hi:[1,0]
	v_rcp_f32_e32 v166, v166
	v_rcp_f32_e32 v167, v167
	v_rcp_f32_e32 v168, v168
	v_rcp_f32_e32 v169, v169
	v_rcp_f32_e32 v170, v170
	v_rcp_f32_e32 v171, v171
	v_rcp_f32_e32 v172, v172
	v_rcp_f32_e32 v173, v173
	v_pk_mul_f32 v[166:167], v[126:127], v[166:167]
	v_pk_mul_f32 v[168:169], v[128:129], v[168:169]
	v_pk_mul_f32 v[170:171], v[122:123], v[170:171]
	v_pk_mul_f32 v[172:173], v[124:125], v[172:173]
	v_pk_mul_f32 v[166:167], v[166:167], v[118:119]
	v_pk_mul_f32 v[168:169], v[168:169], v[120:121]
	v_pk_mul_f32 v[170:171], v[170:171], v[114:115]
	v_pk_mul_f32 v[172:173], v[172:173], v[116:117]
	s_lshl_b32 s3, s46, 1
	s_mul_i32 s2, s24, 44
	s_or_b32 s3, s3, s41
	s_add_i32 s2, s3, s2
	s_ashr_i32 s3, s2, 31
	s_lshl_b64 s[2:3], s[2:3], 15
	v_lshl_add_u64 v[148:149], v[140:141], 0, s[2:3]
	v_cvt_pk_bf16_f32 v114, v166, v167
	v_cvt_pk_bf16_f32 v115, v168, v169
	v_cvt_pk_bf16_f32 v116, v170, v171
	v_cvt_pk_bf16_f32 v117, v172, v173
	global_store_dwordx4 v[148:149], v[114:117], off
	v_pk_mul_f32 v[166:167], v[110:111], s[100:101] op_sel_hi:[1,0]
	v_pk_mul_f32 v[168:169], v[112:113], s[100:101] op_sel_hi:[1,0]
	v_pk_mul_f32 v[170:171], v[106:107], s[100:101] op_sel_hi:[1,0]
	v_pk_mul_f32 v[172:173], v[108:109], s[100:101] op_sel_hi:[1,0]
	v_exp_f32_e32 v166, v166
	v_exp_f32_e32 v167, v167
	v_exp_f32_e32 v168, v168
	v_exp_f32_e32 v169, v169
	v_exp_f32_e32 v170, v170
	v_exp_f32_e32 v171, v171
	v_exp_f32_e32 v172, v172
	v_exp_f32_e32 v173, v173
	v_pk_add_f32 v[166:167], v[166:167], 1.0 op_sel_hi:[1,0]
	v_pk_add_f32 v[168:169], v[168:169], 1.0 op_sel_hi:[1,0]
	v_pk_add_f32 v[170:171], v[170:171], 1.0 op_sel_hi:[1,0]
	v_pk_add_f32 v[172:173], v[172:173], 1.0 op_sel_hi:[1,0]
	v_rcp_f32_e32 v166, v166
	v_rcp_f32_e32 v167, v167
	v_rcp_f32_e32 v168, v168
	v_rcp_f32_e32 v169, v169
	v_rcp_f32_e32 v170, v170
	v_rcp_f32_e32 v171, v171
	v_rcp_f32_e32 v172, v172
	v_rcp_f32_e32 v173, v173
	v_pk_mul_f32 v[166:167], v[110:111], v[166:167]
	v_pk_mul_f32 v[168:169], v[112:113], v[168:169]
	v_pk_mul_f32 v[170:171], v[106:107], v[170:171]
	v_pk_mul_f32 v[172:173], v[108:109], v[172:173]
	v_pk_mul_f32 v[166:167], v[166:167], v[102:103]
	v_pk_mul_f32 v[168:169], v[168:169], v[104:105]
	v_pk_mul_f32 v[170:171], v[170:171], v[98:99]
	v_pk_mul_f32 v[172:173], v[172:173], v[100:101]
	s_mov_b64 s[2:3], -1
	v_cvt_pk_bf16_f32 v98, v166, v167
	v_cvt_pk_bf16_f32 v99, v168, v169
	v_cvt_pk_bf16_f32 v100, v170, v171
	v_cvt_pk_bf16_f32 v101, v172, v173
	global_store_dwordx4 v[148:149], v[98:101], off offset:2048
	v_pk_mul_f32 v[166:167], v[94:95], s[100:101] op_sel_hi:[1,0]
	v_pk_mul_f32 v[168:169], v[96:97], s[100:101] op_sel_hi:[1,0]
	v_pk_mul_f32 v[170:171], v[90:91], s[100:101] op_sel_hi:[1,0]
	v_pk_mul_f32 v[172:173], v[92:93], s[100:101] op_sel_hi:[1,0]
	v_exp_f32_e32 v166, v166
	v_exp_f32_e32 v167, v167
	v_exp_f32_e32 v168, v168
	v_exp_f32_e32 v169, v169
	v_exp_f32_e32 v170, v170
	v_exp_f32_e32 v171, v171
	v_exp_f32_e32 v172, v172
	v_exp_f32_e32 v173, v173
	v_pk_add_f32 v[166:167], v[166:167], 1.0 op_sel_hi:[1,0]
	v_pk_add_f32 v[168:169], v[168:169], 1.0 op_sel_hi:[1,0]
	v_pk_add_f32 v[170:171], v[170:171], 1.0 op_sel_hi:[1,0]
	v_pk_add_f32 v[172:173], v[172:173], 1.0 op_sel_hi:[1,0]
	v_rcp_f32_e32 v166, v166
	v_rcp_f32_e32 v167, v167
	v_rcp_f32_e32 v168, v168
	v_rcp_f32_e32 v169, v169
	v_rcp_f32_e32 v170, v170
	v_rcp_f32_e32 v171, v171
	v_rcp_f32_e32 v172, v172
	v_rcp_f32_e32 v173, v173
	v_pk_mul_f32 v[166:167], v[94:95], v[166:167]
	v_pk_mul_f32 v[168:169], v[96:97], v[168:169]
	v_pk_mul_f32 v[170:171], v[90:91], v[170:171]
	v_pk_mul_f32 v[172:173], v[92:93], v[172:173]
	v_pk_mul_f32 v[166:167], v[166:167], v[86:87]
	v_pk_mul_f32 v[168:169], v[168:169], v[88:89]
	v_pk_mul_f32 v[170:171], v[170:171], v[82:83]
	v_pk_mul_f32 v[172:173], v[172:173], v[84:85]
	v_add_co_u32_e32 v86, vcc, s44, v148
	s_nop 1
	v_addc_co_u32_e32 v87, vcc, 0, v149, vcc
	v_cvt_pk_bf16_f32 v82, v166, v167
	v_cvt_pk_bf16_f32 v83, v168, v169
	v_cvt_pk_bf16_f32 v84, v170, v171
	v_cvt_pk_bf16_f32 v85, v172, v173
	global_store_dwordx4 v[86:87], v[82:85], off
	v_pk_mul_f32 v[166:167], v[78:79], s[100:101] op_sel_hi:[1,0]
	v_pk_mul_f32 v[168:169], v[80:81], s[100:101] op_sel_hi:[1,0]
	v_pk_mul_f32 v[170:171], v[74:75], s[100:101] op_sel_hi:[1,0]
	v_pk_mul_f32 v[172:173], v[76:77], s[100:101] op_sel_hi:[1,0]
	v_exp_f32_e32 v166, v166
	v_exp_f32_e32 v167, v167
	v_exp_f32_e32 v168, v168
	v_exp_f32_e32 v169, v169
	v_exp_f32_e32 v170, v170
	v_exp_f32_e32 v171, v171
	v_exp_f32_e32 v172, v172
	v_exp_f32_e32 v173, v173
	v_pk_add_f32 v[166:167], v[166:167], 1.0 op_sel_hi:[1,0]
	v_pk_add_f32 v[168:169], v[168:169], 1.0 op_sel_hi:[1,0]
	v_pk_add_f32 v[170:171], v[170:171], 1.0 op_sel_hi:[1,0]
	v_pk_add_f32 v[172:173], v[172:173], 1.0 op_sel_hi:[1,0]
	v_rcp_f32_e32 v166, v166
	v_rcp_f32_e32 v167, v167
	v_rcp_f32_e32 v168, v168
	v_rcp_f32_e32 v169, v169
	v_rcp_f32_e32 v170, v170
	v_rcp_f32_e32 v171, v171
	v_rcp_f32_e32 v172, v172
	v_rcp_f32_e32 v173, v173
	v_pk_mul_f32 v[166:167], v[78:79], v[166:167]
	v_pk_mul_f32 v[168:169], v[80:81], v[168:169]
	v_pk_mul_f32 v[170:171], v[74:75], v[170:171]
	v_pk_mul_f32 v[172:173], v[76:77], v[172:173]
	v_pk_mul_f32 v[166:167], v[166:167], v[70:71]
	v_pk_mul_f32 v[168:169], v[168:169], v[72:73]
	v_pk_mul_f32 v[170:171], v[170:171], v[66:67]
	v_pk_mul_f32 v[172:173], v[172:173], v[68:69]
	v_cvt_pk_bf16_f32 v66, v166, v167
	v_cvt_pk_bf16_f32 v67, v168, v169
	v_cvt_pk_bf16_f32 v68, v170, v171
	v_cvt_pk_bf16_f32 v69, v172, v173
	global_store_dwordx4 v[86:87], v[66:69], off offset:2048
	v_pk_mul_f32 v[166:167], v[62:63], s[100:101] op_sel_hi:[1,0]
	v_pk_mul_f32 v[168:169], v[64:65], s[100:101] op_sel_hi:[1,0]
	v_pk_mul_f32 v[170:171], v[58:59], s[100:101] op_sel_hi:[1,0]
	v_pk_mul_f32 v[172:173], v[60:61], s[100:101] op_sel_hi:[1,0]
	v_exp_f32_e32 v166, v166
	v_exp_f32_e32 v167, v167
	v_exp_f32_e32 v168, v168
	v_exp_f32_e32 v169, v169
	v_exp_f32_e32 v170, v170
	v_exp_f32_e32 v171, v171
	v_exp_f32_e32 v172, v172
	v_exp_f32_e32 v173, v173
	v_pk_add_f32 v[166:167], v[166:167], 1.0 op_sel_hi:[1,0]
	v_pk_add_f32 v[168:169], v[168:169], 1.0 op_sel_hi:[1,0]
	v_pk_add_f32 v[170:171], v[170:171], 1.0 op_sel_hi:[1,0]
	v_pk_add_f32 v[172:173], v[172:173], 1.0 op_sel_hi:[1,0]
	v_rcp_f32_e32 v166, v166
	v_rcp_f32_e32 v167, v167
	v_rcp_f32_e32 v168, v168
	v_rcp_f32_e32 v169, v169
	v_rcp_f32_e32 v170, v170
	v_rcp_f32_e32 v171, v171
	v_rcp_f32_e32 v172, v172
	v_rcp_f32_e32 v173, v173
	v_pk_mul_f32 v[166:167], v[62:63], v[166:167]
	v_pk_mul_f32 v[168:169], v[64:65], v[168:169]
	v_pk_mul_f32 v[170:171], v[58:59], v[170:171]
	v_pk_mul_f32 v[172:173], v[60:61], v[172:173]
	v_pk_mul_f32 v[166:167], v[166:167], v[54:55]
	v_pk_mul_f32 v[168:169], v[168:169], v[56:57]
	v_pk_mul_f32 v[170:171], v[170:171], v[50:51]
	v_pk_mul_f32 v[172:173], v[172:173], v[52:53]
	v_add_co_u32_e32 v54, vcc, s38, v148
	s_nop 1
	v_addc_co_u32_e32 v55, vcc, 0, v149, vcc
	v_add_co_u32_e32 v56, vcc, s45, v148
	s_nop 0
	s_nop 1
	v_addc_co_u32_e32 v57, vcc, 0, v149, vcc
	v_cvt_pk_bf16_f32 v50, v166, v167
	v_cvt_pk_bf16_f32 v51, v168, v169
	v_cvt_pk_bf16_f32 v52, v170, v171
	v_cvt_pk_bf16_f32 v53, v172, v173
	global_store_dwordx4 v[56:57], v[50:53], off offset:-4096
	v_pk_mul_f32 v[166:167], v[46:47], s[100:101] op_sel_hi:[1,0]
	v_pk_mul_f32 v[168:169], v[48:49], s[100:101] op_sel_hi:[1,0]
	v_pk_mul_f32 v[170:171], v[42:43], s[100:101] op_sel_hi:[1,0]
	v_pk_mul_f32 v[172:173], v[44:45], s[100:101] op_sel_hi:[1,0]
	v_exp_f32_e32 v166, v166
	v_exp_f32_e32 v167, v167
	v_exp_f32_e32 v168, v168
	v_exp_f32_e32 v169, v169
	v_exp_f32_e32 v170, v170
	v_exp_f32_e32 v171, v171
	v_exp_f32_e32 v172, v172
	v_exp_f32_e32 v173, v173
	v_pk_add_f32 v[166:167], v[166:167], 1.0 op_sel_hi:[1,0]
	v_pk_add_f32 v[168:169], v[168:169], 1.0 op_sel_hi:[1,0]
	v_pk_add_f32 v[170:171], v[170:171], 1.0 op_sel_hi:[1,0]
	v_pk_add_f32 v[172:173], v[172:173], 1.0 op_sel_hi:[1,0]
	v_rcp_f32_e32 v166, v166
	v_rcp_f32_e32 v167, v167
	v_rcp_f32_e32 v168, v168
	v_rcp_f32_e32 v169, v169
	v_rcp_f32_e32 v170, v170
	v_rcp_f32_e32 v171, v171
	v_rcp_f32_e32 v172, v172
	v_rcp_f32_e32 v173, v173
	v_pk_mul_f32 v[166:167], v[46:47], v[166:167]
	v_pk_mul_f32 v[168:169], v[48:49], v[168:169]
	v_pk_mul_f32 v[170:171], v[42:43], v[170:171]
	v_pk_mul_f32 v[172:173], v[44:45], v[172:173]
	v_pk_mul_f32 v[166:167], v[166:167], v[38:39]
	v_pk_mul_f32 v[168:169], v[168:169], v[40:41]
	v_pk_mul_f32 v[170:171], v[170:171], v[34:35]
	v_pk_mul_f32 v[172:173], v[172:173], v[36:37]
	s_andn2_b64 vcc, exec, s[18:19]
	v_cvt_pk_bf16_f32 v34, v166, v167
	v_cvt_pk_bf16_f32 v35, v168, v169
	v_cvt_pk_bf16_f32 v36, v170, v171
	v_cvt_pk_bf16_f32 v37, v172, v173
	global_store_dwordx4 v[54:55], v[34:37], off offset:2048
	v_pk_mul_f32 v[166:167], v[30:31], s[100:101] op_sel_hi:[1,0]
	v_pk_mul_f32 v[168:169], v[32:33], s[100:101] op_sel_hi:[1,0]
	v_pk_mul_f32 v[170:171], v[26:27], s[100:101] op_sel_hi:[1,0]
	v_pk_mul_f32 v[172:173], v[28:29], s[100:101] op_sel_hi:[1,0]
	v_exp_f32_e32 v166, v166
	v_exp_f32_e32 v167, v167
	v_exp_f32_e32 v168, v168
	v_exp_f32_e32 v169, v169
	v_exp_f32_e32 v170, v170
	v_exp_f32_e32 v171, v171
	v_exp_f32_e32 v172, v172
	v_exp_f32_e32 v173, v173
	v_pk_add_f32 v[166:167], v[166:167], 1.0 op_sel_hi:[1,0]
	v_pk_add_f32 v[168:169], v[168:169], 1.0 op_sel_hi:[1,0]
	v_pk_add_f32 v[170:171], v[170:171], 1.0 op_sel_hi:[1,0]
	v_pk_add_f32 v[172:173], v[172:173], 1.0 op_sel_hi:[1,0]
	v_rcp_f32_e32 v166, v166
	v_rcp_f32_e32 v167, v167
	v_rcp_f32_e32 v168, v168
	v_rcp_f32_e32 v169, v169
	v_rcp_f32_e32 v170, v170
	v_rcp_f32_e32 v171, v171
	v_rcp_f32_e32 v172, v172
	v_rcp_f32_e32 v173, v173
	v_pk_mul_f32 v[166:167], v[30:31], v[166:167]
	v_pk_mul_f32 v[168:169], v[32:33], v[168:169]
	v_pk_mul_f32 v[170:171], v[26:27], v[170:171]
	v_pk_mul_f32 v[172:173], v[28:29], v[172:173]
	v_pk_mul_f32 v[166:167], v[166:167], v[22:23]
	v_pk_mul_f32 v[168:169], v[168:169], v[24:25]
	v_pk_mul_f32 v[170:171], v[170:171], v[18:19]
	v_pk_mul_f32 v[172:173], v[172:173], v[20:21]
	v_cvt_pk_bf16_f32 v18, v166, v167
	v_cvt_pk_bf16_f32 v19, v168, v169
	v_cvt_pk_bf16_f32 v20, v170, v171
	v_cvt_pk_bf16_f32 v21, v172, v173
	global_store_dwordx4 v[56:57], v[18:21], off
	v_pk_mul_f32 v[166:167], v[14:15], s[100:101] op_sel_hi:[1,0]
	v_pk_mul_f32 v[168:169], v[16:17], s[100:101] op_sel_hi:[1,0]
	v_pk_mul_f32 v[170:171], v[10:11], s[100:101] op_sel_hi:[1,0]
	v_pk_mul_f32 v[172:173], v[12:13], s[100:101] op_sel_hi:[1,0]
	v_exp_f32_e32 v166, v166
	v_exp_f32_e32 v167, v167
	v_exp_f32_e32 v168, v168
	v_exp_f32_e32 v169, v169
	v_exp_f32_e32 v170, v170
	v_exp_f32_e32 v171, v171
	v_exp_f32_e32 v172, v172
	v_exp_f32_e32 v173, v173
	v_pk_add_f32 v[166:167], v[166:167], 1.0 op_sel_hi:[1,0]
	v_pk_add_f32 v[168:169], v[168:169], 1.0 op_sel_hi:[1,0]
	v_pk_add_f32 v[170:171], v[170:171], 1.0 op_sel_hi:[1,0]
	v_pk_add_f32 v[172:173], v[172:173], 1.0 op_sel_hi:[1,0]
	v_rcp_f32_e32 v166, v166
	v_rcp_f32_e32 v167, v167
	v_rcp_f32_e32 v168, v168
	v_rcp_f32_e32 v169, v169
	v_rcp_f32_e32 v170, v170
	v_rcp_f32_e32 v171, v171
	v_rcp_f32_e32 v172, v172
	v_rcp_f32_e32 v173, v173
	v_pk_mul_f32 v[166:167], v[14:15], v[166:167]
	v_pk_mul_f32 v[168:169], v[16:17], v[168:169]
	v_pk_mul_f32 v[170:171], v[10:11], v[170:171]
	v_pk_mul_f32 v[172:173], v[12:13], v[172:173]
	v_pk_mul_f32 v[166:167], v[166:167], v[6:7]
	v_pk_mul_f32 v[168:169], v[168:169], v[8:9]
	v_pk_mul_f32 v[170:171], v[170:171], v[2:3]
	v_pk_mul_f32 v[172:173], v[172:173], v[4:5]
	v_cvt_pk_bf16_f32 v2, v166, v167
	v_cvt_pk_bf16_f32 v3, v168, v169
	v_cvt_pk_bf16_f32 v4, v170, v171
	v_cvt_pk_bf16_f32 v5, v172, v173
	global_store_dwordx4 v[56:57], v[2:5], off offset:2048
	s_cbranch_vccnz .LBB0_1298
	s_andn2_b64 vcc, exec, s[0:1]
	s_cbranch_vccnz .LBB0_1297
	s_barrier
	s_branch .LBB0_1297

.LBB0_1403:
	s_mov_b32 s100, 0xbfb8aa3b
	v_pk_mul_f32 v[152:153], v[126:127], s[100:101] op_sel_hi:[1,0]
	v_pk_mul_f32 v[154:155], v[128:129], s[100:101] op_sel_hi:[1,0]
	v_pk_mul_f32 v[156:157], v[122:123], s[100:101] op_sel_hi:[1,0]
	v_pk_mul_f32 v[158:159], v[124:125], s[100:101] op_sel_hi:[1,0]
	v_exp_f32_e32 v152, v152
	v_exp_f32_e32 v153, v153
	v_exp_f32_e32 v154, v154
	v_exp_f32_e32 v155, v155
	v_exp_f32_e32 v156, v156
	v_exp_f32_e32 v157, v157
	v_exp_f32_e32 v158, v158
	v_exp_f32_e32 v159, v159
	v_pk_add_f32 v[152:153], v[152:153], 1.0 op_sel_hi:[1,0]
	v_pk_add_f32 v[154:155], v[154:155], 1.0 op_sel_hi:[1,0]
	v_pk_add_f32 v[156:157], v[156:157], 1.0 op_sel_hi:[1,0]
	v_pk_add_f32 v[158:159], v[158:159], 1.0 op_sel_hi:[1,0]
	v_rcp_f32_e32 v152, v152
	v_rcp_f32_e32 v153, v153
	v_rcp_f32_e32 v154, v154
	v_rcp_f32_e32 v155, v155
	v_rcp_f32_e32 v156, v156
	v_rcp_f32_e32 v157, v157
	v_rcp_f32_e32 v158, v158
	v_rcp_f32_e32 v159, v159
	v_pk_mul_f32 v[152:153], v[126:127], v[152:153]
	v_pk_mul_f32 v[154:155], v[128:129], v[154:155]
	v_pk_mul_f32 v[156:157], v[122:123], v[156:157]
	v_pk_mul_f32 v[158:159], v[124:125], v[158:159]
	v_pk_mul_f32 v[152:153], v[152:153], v[118:119]
	v_pk_mul_f32 v[154:155], v[154:155], v[120:121]
	v_pk_mul_f32 v[156:157], v[156:157], v[114:115]
	v_pk_mul_f32 v[158:159], v[158:159], v[116:117]
	s_lshl_b32 s3, s24, 1
	s_mul_i32 s2, s26, 44
	s_or_b32 s3, s3, s42
	s_add_i32 s2, s3, s2
	s_ashr_i32 s3, s2, 31
	s_lshl_b64 s[2:3], s[2:3], 15
	v_lshl_add_u64 v[146:147], v[138:139], 0, s[2:3]
	v_cvt_pk_bf16_f32 v114, v152, v153
	v_cvt_pk_bf16_f32 v115, v154, v155
	v_cvt_pk_bf16_f32 v116, v156, v157
	v_cvt_pk_bf16_f32 v117, v158, v159
	global_store_dwordx4 v[146:147], v[114:117], off
	v_pk_mul_f32 v[152:153], v[110:111], s[100:101] op_sel_hi:[1,0]
	v_pk_mul_f32 v[154:155], v[112:113], s[100:101] op_sel_hi:[1,0]
	v_pk_mul_f32 v[156:157], v[106:107], s[100:101] op_sel_hi:[1,0]
	v_pk_mul_f32 v[158:159], v[108:109], s[100:101] op_sel_hi:[1,0]
	v_exp_f32_e32 v152, v152
	v_exp_f32_e32 v153, v153
	v_exp_f32_e32 v154, v154
	v_exp_f32_e32 v155, v155
	v_exp_f32_e32 v156, v156
	v_exp_f32_e32 v157, v157
	v_exp_f32_e32 v158, v158
	v_exp_f32_e32 v159, v159
	v_pk_add_f32 v[152:153], v[152:153], 1.0 op_sel_hi:[1,0]
	v_pk_add_f32 v[154:155], v[154:155], 1.0 op_sel_hi:[1,0]
	v_pk_add_f32 v[156:157], v[156:157], 1.0 op_sel_hi:[1,0]
	v_pk_add_f32 v[158:159], v[158:159], 1.0 op_sel_hi:[1,0]
	v_rcp_f32_e32 v152, v152
	v_rcp_f32_e32 v153, v153
	v_rcp_f32_e32 v154, v154
	v_rcp_f32_e32 v155, v155
	v_rcp_f32_e32 v156, v156
	v_rcp_f32_e32 v157, v157
	v_rcp_f32_e32 v158, v158
	v_rcp_f32_e32 v159, v159
	v_pk_mul_f32 v[152:153], v[110:111], v[152:153]
	v_pk_mul_f32 v[154:155], v[112:113], v[154:155]
	v_pk_mul_f32 v[156:157], v[106:107], v[156:157]
	v_pk_mul_f32 v[158:159], v[108:109], v[158:159]
	v_pk_mul_f32 v[152:153], v[152:153], v[102:103]
	v_pk_mul_f32 v[154:155], v[154:155], v[104:105]
	v_pk_mul_f32 v[156:157], v[156:157], v[98:99]
	v_pk_mul_f32 v[158:159], v[158:159], v[100:101]
	s_mov_b64 s[2:3], -1
	v_cvt_pk_bf16_f32 v98, v152, v153
	v_cvt_pk_bf16_f32 v99, v154, v155
	v_cvt_pk_bf16_f32 v100, v156, v157
	v_cvt_pk_bf16_f32 v101, v158, v159
	global_store_dwordx4 v[146:147], v[98:101], off offset:2048
	v_pk_mul_f32 v[152:153], v[94:95], s[100:101] op_sel_hi:[1,0]
	v_pk_mul_f32 v[154:155], v[96:97], s[100:101] op_sel_hi:[1,0]
	v_pk_mul_f32 v[156:157], v[90:91], s[100:101] op_sel_hi:[1,0]
	v_pk_mul_f32 v[158:159], v[92:93], s[100:101] op_sel_hi:[1,0]
	v_exp_f32_e32 v152, v152
	v_exp_f32_e32 v153, v153
	v_exp_f32_e32 v154, v154
	v_exp_f32_e32 v155, v155
	v_exp_f32_e32 v156, v156
	v_exp_f32_e32 v157, v157
	v_exp_f32_e32 v158, v158
	v_exp_f32_e32 v159, v159
	v_pk_add_f32 v[152:153], v[152:153], 1.0 op_sel_hi:[1,0]
	v_pk_add_f32 v[154:155], v[154:155], 1.0 op_sel_hi:[1,0]
	v_pk_add_f32 v[156:157], v[156:157], 1.0 op_sel_hi:[1,0]
	v_pk_add_f32 v[158:159], v[158:159], 1.0 op_sel_hi:[1,0]
	v_rcp_f32_e32 v152, v152
	v_rcp_f32_e32 v153, v153
	v_rcp_f32_e32 v154, v154
	v_rcp_f32_e32 v155, v155
	v_rcp_f32_e32 v156, v156
	v_rcp_f32_e32 v157, v157
	v_rcp_f32_e32 v158, v158
	v_rcp_f32_e32 v159, v159
	v_pk_mul_f32 v[152:153], v[94:95], v[152:153]
	v_pk_mul_f32 v[154:155], v[96:97], v[154:155]
	v_pk_mul_f32 v[156:157], v[90:91], v[156:157]
	v_pk_mul_f32 v[158:159], v[92:93], v[158:159]
	v_pk_mul_f32 v[152:153], v[152:153], v[86:87]
	v_pk_mul_f32 v[154:155], v[154:155], v[88:89]
	v_pk_mul_f32 v[156:157], v[156:157], v[82:83]
	v_pk_mul_f32 v[158:159], v[158:159], v[84:85]
	v_add_co_u32_e32 v86, vcc, s45, v146
	s_nop 1
	v_addc_co_u32_e32 v87, vcc, 0, v147, vcc
	v_cvt_pk_bf16_f32 v82, v152, v153
	v_cvt_pk_bf16_f32 v83, v154, v155
	v_cvt_pk_bf16_f32 v84, v156, v157
	v_cvt_pk_bf16_f32 v85, v158, v159
	global_store_dwordx4 v[86:87], v[82:85], off
	v_pk_mul_f32 v[152:153], v[78:79], s[100:101] op_sel_hi:[1,0]
	v_pk_mul_f32 v[154:155], v[80:81], s[100:101] op_sel_hi:[1,0]
	v_pk_mul_f32 v[156:157], v[74:75], s[100:101] op_sel_hi:[1,0]
	v_pk_mul_f32 v[158:159], v[76:77], s[100:101] op_sel_hi:[1,0]
	v_exp_f32_e32 v152, v152
	v_exp_f32_e32 v153, v153
	v_exp_f32_e32 v154, v154
	v_exp_f32_e32 v155, v155
	v_exp_f32_e32 v156, v156
	v_exp_f32_e32 v157, v157
	v_exp_f32_e32 v158, v158
	v_exp_f32_e32 v159, v159
	v_pk_add_f32 v[152:153], v[152:153], 1.0 op_sel_hi:[1,0]
	v_pk_add_f32 v[154:155], v[154:155], 1.0 op_sel_hi:[1,0]
	v_pk_add_f32 v[156:157], v[156:157], 1.0 op_sel_hi:[1,0]
	v_pk_add_f32 v[158:159], v[158:159], 1.0 op_sel_hi:[1,0]
	v_rcp_f32_e32 v152, v152
	v_rcp_f32_e32 v153, v153
	v_rcp_f32_e32 v154, v154
	v_rcp_f32_e32 v155, v155
	v_rcp_f32_e32 v156, v156
	v_rcp_f32_e32 v157, v157
	v_rcp_f32_e32 v158, v158
	v_rcp_f32_e32 v159, v159
	v_pk_mul_f32 v[152:153], v[78:79], v[152:153]
	v_pk_mul_f32 v[154:155], v[80:81], v[154:155]
	v_pk_mul_f32 v[156:157], v[74:75], v[156:157]
	v_pk_mul_f32 v[158:159], v[76:77], v[158:159]
	v_pk_mul_f32 v[152:153], v[152:153], v[70:71]
	v_pk_mul_f32 v[154:155], v[154:155], v[72:73]
	v_pk_mul_f32 v[156:157], v[156:157], v[66:67]
	v_pk_mul_f32 v[158:159], v[158:159], v[68:69]
	v_cvt_pk_bf16_f32 v66, v152, v153
	v_cvt_pk_bf16_f32 v67, v154, v155
	v_cvt_pk_bf16_f32 v68, v156, v157
	v_cvt_pk_bf16_f32 v69, v158, v159
	global_store_dwordx4 v[86:87], v[66:69], off offset:2048
	v_pk_mul_f32 v[152:153], v[62:63], s[100:101] op_sel_hi:[1,0]
	v_pk_mul_f32 v[154:155], v[64:65], s[100:101] op_sel_hi:[1,0]
	v_pk_mul_f32 v[156:157], v[58:59], s[100:101] op_sel_hi:[1,0]
	v_pk_mul_f32 v[158:159], v[60:61], s[100:101] op_sel_hi:[1,0]
	v_exp_f32_e32 v152, v152
	v_exp_f32_e32 v153, v153
	v_exp_f32_e32 v154, v154
	v_exp_f32_e32 v155, v155
	v_exp_f32_e32 v156, v156
	v_exp_f32_e32 v157, v157
	v_exp_f32_e32 v158, v158
	v_exp_f32_e32 v159, v159
	v_pk_add_f32 v[152:153], v[152:153], 1.0 op_sel_hi:[1,0]
	v_pk_add_f32 v[154:155], v[154:155], 1.0 op_sel_hi:[1,0]
	v_pk_add_f32 v[156:157], v[156:157], 1.0 op_sel_hi:[1,0]
	v_pk_add_f32 v[158:159], v[158:159], 1.0 op_sel_hi:[1,0]
	v_rcp_f32_e32 v152, v152
	v_rcp_f32_e32 v153, v153
	v_rcp_f32_e32 v154, v154
	v_rcp_f32_e32 v155, v155
	v_rcp_f32_e32 v156, v156
	v_rcp_f32_e32 v157, v157
	v_rcp_f32_e32 v158, v158
	v_rcp_f32_e32 v159, v159
	v_pk_mul_f32 v[152:153], v[62:63], v[152:153]
	v_pk_mul_f32 v[154:155], v[64:65], v[154:155]
	v_pk_mul_f32 v[156:157], v[58:59], v[156:157]
	v_pk_mul_f32 v[158:159], v[60:61], v[158:159]
	v_pk_mul_f32 v[152:153], v[152:153], v[54:55]
	v_pk_mul_f32 v[154:155], v[154:155], v[56:57]
	v_pk_mul_f32 v[156:157], v[156:157], v[50:51]
	v_pk_mul_f32 v[158:159], v[158:159], v[52:53]
	v_add_co_u32_e32 v54, vcc, s39, v146
	s_nop 1
	v_addc_co_u32_e32 v55, vcc, 0, v147, vcc
	v_add_co_u32_e32 v56, vcc, s46, v146
	s_nop 0
	s_nop 1
	v_addc_co_u32_e32 v57, vcc, 0, v147, vcc
	v_cvt_pk_bf16_f32 v50, v152, v153
	v_cvt_pk_bf16_f32 v51, v154, v155
	v_cvt_pk_bf16_f32 v52, v156, v157
	v_cvt_pk_bf16_f32 v53, v158, v159
	global_store_dwordx4 v[56:57], v[50:53], off offset:-4096
	v_pk_mul_f32 v[152:153], v[46:47], s[100:101] op_sel_hi:[1,0]
	v_pk_mul_f32 v[154:155], v[48:49], s[100:101] op_sel_hi:[1,0]
	v_pk_mul_f32 v[156:157], v[42:43], s[100:101] op_sel_hi:[1,0]
	v_pk_mul_f32 v[158:159], v[44:45], s[100:101] op_sel_hi:[1,0]
	v_exp_f32_e32 v152, v152
	v_exp_f32_e32 v153, v153
	v_exp_f32_e32 v154, v154
	v_exp_f32_e32 v155, v155
	v_exp_f32_e32 v156, v156
	v_exp_f32_e32 v157, v157
	v_exp_f32_e32 v158, v158
	v_exp_f32_e32 v159, v159
	v_pk_add_f32 v[152:153], v[152:153], 1.0 op_sel_hi:[1,0]
	v_pk_add_f32 v[154:155], v[154:155], 1.0 op_sel_hi:[1,0]
	v_pk_add_f32 v[156:157], v[156:157], 1.0 op_sel_hi:[1,0]
	v_pk_add_f32 v[158:159], v[158:159], 1.0 op_sel_hi:[1,0]
	v_rcp_f32_e32 v152, v152
	v_rcp_f32_e32 v153, v153
	v_rcp_f32_e32 v154, v154
	v_rcp_f32_e32 v155, v155
	v_rcp_f32_e32 v156, v156
	v_rcp_f32_e32 v157, v157
	v_rcp_f32_e32 v158, v158
	v_rcp_f32_e32 v159, v159
	v_pk_mul_f32 v[152:153], v[46:47], v[152:153]
	v_pk_mul_f32 v[154:155], v[48:49], v[154:155]
	v_pk_mul_f32 v[156:157], v[42:43], v[156:157]
	v_pk_mul_f32 v[158:159], v[44:45], v[158:159]
	v_pk_mul_f32 v[152:153], v[152:153], v[38:39]
	v_pk_mul_f32 v[154:155], v[154:155], v[40:41]
	v_pk_mul_f32 v[156:157], v[156:157], v[34:35]
	v_pk_mul_f32 v[158:159], v[158:159], v[36:37]
	s_andn2_b64 vcc, exec, s[18:19]
	v_cvt_pk_bf16_f32 v34, v152, v153
	v_cvt_pk_bf16_f32 v35, v154, v155
	v_cvt_pk_bf16_f32 v36, v156, v157
	v_cvt_pk_bf16_f32 v37, v158, v159
	global_store_dwordx4 v[54:55], v[34:37], off offset:2048
	v_pk_mul_f32 v[152:153], v[30:31], s[100:101] op_sel_hi:[1,0]
	v_pk_mul_f32 v[154:155], v[32:33], s[100:101] op_sel_hi:[1,0]
	v_pk_mul_f32 v[156:157], v[26:27], s[100:101] op_sel_hi:[1,0]
	v_pk_mul_f32 v[158:159], v[28:29], s[100:101] op_sel_hi:[1,0]
	v_exp_f32_e32 v152, v152
	v_exp_f32_e32 v153, v153
	v_exp_f32_e32 v154, v154
	v_exp_f32_e32 v155, v155
	v_exp_f32_e32 v156, v156
	v_exp_f32_e32 v157, v157
	v_exp_f32_e32 v158, v158
	v_exp_f32_e32 v159, v159
	v_pk_add_f32 v[152:153], v[152:153], 1.0 op_sel_hi:[1,0]
	v_pk_add_f32 v[154:155], v[154:155], 1.0 op_sel_hi:[1,0]
	v_pk_add_f32 v[156:157], v[156:157], 1.0 op_sel_hi:[1,0]
	v_pk_add_f32 v[158:159], v[158:159], 1.0 op_sel_hi:[1,0]
	v_rcp_f32_e32 v152, v152
	v_rcp_f32_e32 v153, v153
	v_rcp_f32_e32 v154, v154
	v_rcp_f32_e32 v155, v155
	v_rcp_f32_e32 v156, v156
	v_rcp_f32_e32 v157, v157
	v_rcp_f32_e32 v158, v158
	v_rcp_f32_e32 v159, v159
	v_pk_mul_f32 v[152:153], v[30:31], v[152:153]
	v_pk_mul_f32 v[154:155], v[32:33], v[154:155]
	v_pk_mul_f32 v[156:157], v[26:27], v[156:157]
	v_pk_mul_f32 v[158:159], v[28:29], v[158:159]
	v_pk_mul_f32 v[152:153], v[152:153], v[22:23]
	v_pk_mul_f32 v[154:155], v[154:155], v[24:25]
	v_pk_mul_f32 v[156:157], v[156:157], v[18:19]
	v_pk_mul_f32 v[158:159], v[158:159], v[20:21]
	v_cvt_pk_bf16_f32 v18, v152, v153
	v_cvt_pk_bf16_f32 v19, v154, v155
	v_cvt_pk_bf16_f32 v20, v156, v157
	v_cvt_pk_bf16_f32 v21, v158, v159
	global_store_dwordx4 v[56:57], v[18:21], off
	v_pk_mul_f32 v[152:153], v[14:15], s[100:101] op_sel_hi:[1,0]
	v_pk_mul_f32 v[154:155], v[16:17], s[100:101] op_sel_hi:[1,0]
	v_pk_mul_f32 v[156:157], v[10:11], s[100:101] op_sel_hi:[1,0]
	v_pk_mul_f32 v[158:159], v[12:13], s[100:101] op_sel_hi:[1,0]
	v_exp_f32_e32 v152, v152
	v_exp_f32_e32 v153, v153
	v_exp_f32_e32 v154, v154
	v_exp_f32_e32 v155, v155
	v_exp_f32_e32 v156, v156
	v_exp_f32_e32 v157, v157
	v_exp_f32_e32 v158, v158
	v_exp_f32_e32 v159, v159
	v_pk_add_f32 v[152:153], v[152:153], 1.0 op_sel_hi:[1,0]
	v_pk_add_f32 v[154:155], v[154:155], 1.0 op_sel_hi:[1,0]
	v_pk_add_f32 v[156:157], v[156:157], 1.0 op_sel_hi:[1,0]
	v_pk_add_f32 v[158:159], v[158:159], 1.0 op_sel_hi:[1,0]
	v_rcp_f32_e32 v152, v152
	v_rcp_f32_e32 v153, v153
	v_rcp_f32_e32 v154, v154
	v_rcp_f32_e32 v155, v155
	v_rcp_f32_e32 v156, v156
	v_rcp_f32_e32 v157, v157
	v_rcp_f32_e32 v158, v158
	v_rcp_f32_e32 v159, v159
	v_pk_mul_f32 v[152:153], v[14:15], v[152:153]
	v_pk_mul_f32 v[154:155], v[16:17], v[154:155]
	v_pk_mul_f32 v[156:157], v[10:11], v[156:157]
	v_pk_mul_f32 v[158:159], v[12:13], v[158:159]
	v_pk_mul_f32 v[152:153], v[152:153], v[6:7]
	v_pk_mul_f32 v[154:155], v[154:155], v[8:9]
	v_pk_mul_f32 v[156:157], v[156:157], v[2:3]
	v_pk_mul_f32 v[158:159], v[158:159], v[4:5]
	v_cvt_pk_bf16_f32 v2, v152, v153
	v_cvt_pk_bf16_f32 v3, v154, v155
	v_cvt_pk_bf16_f32 v4, v156, v157
	v_cvt_pk_bf16_f32 v5, v158, v159
	global_store_dwordx4 v[56:57], v[2:5], off offset:2048
	s_cbranch_vccnz .LBB0_1395
	s_andn2_b64 vcc, exec, s[0:1]
	s_cbranch_vccnz .LBB0_1394
	s_barrier
	s_branch .LBB0_1394
